# attention sample logits: fused pass over dim quads, q read once per quad for all three key rounds, key quads streamed 21 deep, q loads batched
# speedup vs baseline: 1.1901x; 1.0047x over previous
; #define LAS __attribute__((address_space(3)))
; DI float bf2f(bf16_t b) { return __uint_as_float((unsigned)b << 16); }
; DI void attn_sample_task(LAS unsigned char* wl, int task, int l, ArgsP a, const bf16_t* Q, bf16_t* YB, int lane) {
;     const int b = task >> 3, h = task & 7, g = h >> 2;
;     LAS float* qs = (LAS float*)wl;
;     LAS float* ps = qs + 256;
; #pragma unroll
;     for (int t = 0; t < 4; ++t) qs[t * 64 + lane] = bf2f(Q[(size_t)(MP + b * 4 + t) * 512 + h * 64 + lane]);
;     const float* ck = a->in[2] + (size_t)(l * 128 + b) * 128 * 128 + g * 64;
;     const float* cv = a->in[3] + (size_t)(l * 128 + b) * 128 * 128 + g * 64;
;     const float* nk = a->out + OFF_KS + ((size_t)(l * 128 + b) * 128 + 124) * 128 + g * 64;
;     const float* nv = a->out + OFF_VS + ((size_t)(l * 128 + b) * 128 + 124) * 128 + g * 64;
;     const float sink = a->in[16][l * 8 + h];
;     float mx[4] = {sink, sink, sink, sink};
;     for (int rr = 0; rr < 3; ++rr) { const int j = rr * 64 + lane; float s[4] = {0.f, 0.f, 0.f, 0.f};
;         if (j < 132) { const float* kp = j < 128 ? ck + (size_t)j * 128 : nk + (size_t)(j - 128) * 128;
; #pragma unroll 4
;             for (int d4 = 0; d4 < 16; ++d4) { const f32x4 k4 = *(const f32x4*)(kp + 4 * d4);
; #pragma unroll
;                 for (int t = 0; t < 4; ++t) { const f32x4 q4 = *(const LAS f32x4*)(qs + t * 64 + 4 * d4); s[t] += k4[0] * q4[0] + k4[1] * q4[1] + k4[2] * q4[2] + k4[3] * q4[3]; } } }
.LBB0_968:
	v_ashrrev_i32_e32 v4, 3, v100
	v_lshlrev_b32_e32 v0, 2, v4
	v_ashrrev_i32_e32 v1, 31, v0
	v_lshlrev_b64 v[0:1], 10, v[0:1]
	s_mov_b64 s[2:3], 0x1000000
	v_lshl_add_u64 v[30:31], v[0:1], 0, s[2:3]
	s_mov_b64 s[2:3], 0x1000400
	v_lshl_add_u64 v[28:29], v[0:1], 0, s[2:3]
	s_mov_b64 s[2:3], 0x1000800
	v_lshl_add_u64 v[26:27], v[0:1], 0, s[2:3]
	s_mov_b64 s[2:3], 0x1000c00
	v_lshl_add_u64 v[24:25], v[0:1], 0, s[2:3]
	v_lshl_add_u64 v[32:33], v[8:9], 0, v[30:31]
	global_load_ushort v5, v[32:33], off
	v_lshl_add_u64 v[32:33], v[8:9], 0, v[28:29]
	global_load_ushort v6, v[32:33], off
	v_lshl_add_u64 v[32:33], v[8:9], 0, v[26:27]
	global_load_ushort v7, v[32:33], off
	v_lshl_add_u64 v[32:33], v[8:9], 0, v[24:25]
	global_load_ushort v42, v[32:33], off
	v_add_u32_e32 v0, s87, v4
	v_ashrrev_i32_e32 v1, 31, v0
	v_lshlrev_b64 v[0:1], 16, v[0:1]
	v_lshl_add_u64 v[2:3], v[14:15], 0, v[0:1]
	v_lshl_add_u64 v[44:45], v[16:17], 0, v[0:1]
	v_lshl_add_u64 v[50:51], v[18:19], 0, v[0:1]
	v_cndmask_b32_e64 v48, v2, v50, s[14:15]
	v_cndmask_b32_e64 v49, v3, v51, s[14:15]
	global_load_dwordx4 v[198:201], v[2:3], off offset:-32
	global_load_dwordx4 v[202:205], v[44:45], off offset:-32
	global_load_dwordx4 v[206:209], v[48:49], off offset:-32
	global_load_dwordx4 v[210:213], v[2:3], off offset:-16
	global_load_dwordx4 v[214:217], v[44:45], off offset:-16
	global_load_dwordx4 v[218:221], v[48:49], off offset:-16
	global_load_dwordx4 v[222:225], v[2:3], off
	global_load_dwordx4 v[226:229], v[44:45], off
	global_load_dwordx4 v[230:233], v[48:49], off
	global_load_dwordx4 v[234:237], v[2:3], off offset:16
	global_load_dwordx4 v[238:241], v[44:45], off offset:16
	global_load_dwordx4 v[242:245], v[48:49], off offset:16
	global_load_dwordx4 v[246:249], v[2:3], off offset:32
	global_load_dwordx4 v[250:253], v[44:45], off offset:32
	global_load_dwordx4 v[182:185], v[48:49], off offset:32
	global_load_dwordx4 v[186:189], v[2:3], off offset:48
	global_load_dwordx4 v[190:193], v[44:45], off offset:48
	global_load_dwordx4 v[156:159], v[48:49], off offset:48
	global_load_dwordx4 v[160:163], v[2:3], off offset:64
	global_load_dwordx4 v[170:173], v[44:45], off offset:64
	global_load_dwordx4 v[174:177], v[48:49], off offset:64
	s_waitcnt vmcnt(21)
	v_lshlrev_b32_e32 v5, 16, v5
	v_lshlrev_b32_e32 v6, 16, v6
	v_lshlrev_b32_e32 v7, 16, v7
	v_lshlrev_b32_e32 v42, 16, v42
	ds_write2st64_b32 v47, v5, v6 offset1:1
	ds_write2st64_b32 v47, v7, v42 offset0:2 offset1:3
	v_mov_b32_e32 v4, 0
	v_mov_b32_e32 v5, 0
	v_mov_b32_e32 v6, 0
	v_mov_b32_e32 v7, 0
	v_mov_b32_e32 v148, 0
	v_mov_b32_e32 v149, 0
	v_mov_b32_e32 v150, 0
	v_mov_b32_e32 v151, 0
	v_mov_b32_e32 v152, 0
	v_mov_b32_e32 v153, 0
	v_mov_b32_e32 v154, 0
	v_mov_b32_e32 v155, 0
	ds_read_b128 v[70:73], v43
	ds_read_b128 v[74:77], v43 offset:256
	ds_read_b128 v[78:81], v43 offset:512
	ds_read_b128 v[82:85], v43 offset:768
	ds_read_b128 v[32:35], v43 offset:16
	ds_read_b128 v[36:39], v43 offset:272
	ds_read_b128 v[54:57], v43 offset:528
	ds_read_b128 v[60:63], v43 offset:784
	s_waitcnt vmcnt(18)
	s_waitcnt lgkmcnt(4)
	v_fmac_f32_e32 v4, v198, v70
	v_fmac_f32_e32 v5, v198, v74
	v_fmac_f32_e32 v6, v198, v78
	v_fmac_f32_e32 v7, v198, v82
	v_fmac_f32_e32 v148, v202, v70
	v_fmac_f32_e32 v149, v202, v74
	v_fmac_f32_e32 v150, v202, v78
	v_fmac_f32_e32 v151, v202, v82
	v_fmac_f32_e32 v152, v206, v70
	v_fmac_f32_e32 v153, v206, v74
	v_fmac_f32_e32 v154, v206, v78
	v_fmac_f32_e32 v155, v206, v82
	v_fmac_f32_e32 v4, v199, v71
	v_fmac_f32_e32 v5, v199, v75
	v_fmac_f32_e32 v6, v199, v79
	v_fmac_f32_e32 v7, v199, v83
	v_fmac_f32_e32 v148, v203, v71
	v_fmac_f32_e32 v149, v203, v75
	v_fmac_f32_e32 v150, v203, v79
	v_fmac_f32_e32 v151, v203, v83
	v_fmac_f32_e32 v152, v207, v71
	v_fmac_f32_e32 v153, v207, v75
	v_fmac_f32_e32 v154, v207, v79
	v_fmac_f32_e32 v155, v207, v83
	v_fmac_f32_e32 v4, v200, v72
	v_fmac_f32_e32 v5, v200, v76
	v_fmac_f32_e32 v6, v200, v80
	v_fmac_f32_e32 v7, v200, v84
	v_fmac_f32_e32 v148, v204, v72
	v_fmac_f32_e32 v149, v204, v76
	v_fmac_f32_e32 v150, v204, v80
	v_fmac_f32_e32 v151, v204, v84
	v_fmac_f32_e32 v152, v208, v72
	v_fmac_f32_e32 v153, v208, v76
	v_fmac_f32_e32 v154, v208, v80
	v_fmac_f32_e32 v155, v208, v84
	v_fmac_f32_e32 v4, v201, v73
	v_fmac_f32_e32 v5, v201, v77
	v_fmac_f32_e32 v6, v201, v81
	v_fmac_f32_e32 v7, v201, v85
	v_fmac_f32_e32 v148, v205, v73
	v_fmac_f32_e32 v149, v205, v77
	v_fmac_f32_e32 v150, v205, v81
	v_fmac_f32_e32 v151, v205, v85
	v_fmac_f32_e32 v152, v209, v73
	v_fmac_f32_e32 v153, v209, v77
	v_fmac_f32_e32 v154, v209, v81
	v_fmac_f32_e32 v155, v209, v85
	global_load_dwordx4 v[198:201], v[2:3], off offset:80
	global_load_dwordx4 v[202:205], v[44:45], off offset:80
	global_load_dwordx4 v[206:209], v[48:49], off offset:80
	ds_read_b128 v[70:73], v43 offset:32
	ds_read_b128 v[74:77], v43 offset:288
	ds_read_b128 v[78:81], v43 offset:544
	ds_read_b128 v[82:85], v43 offset:800
	s_waitcnt vmcnt(18)
	s_waitcnt lgkmcnt(4)
; #define LAS __attribute__((address_space(3)))
; DI void attn_sample_task(LAS unsigned char* wl, int task, int l, ArgsP a, const bf16_t* Q, bf16_t* YB, int lane) {
;     ...
;     for (int rr = 0; rr < 3; ++rr) { const int j = rr * 64 + lane; float s[4] = {0.f, 0.f, 0.f, 0.f};
;         if (j < 132) { const float* kp = j < 128 ? ck + (size_t)j * 128 : nk + (size_t)(j - 128) * 128;
; #pragma unroll 4
;             for (int d4 = 0; d4 < 16; ++d4) { const f32x4 k4 = *(const f32x4*)(kp + 4 * d4);
; #pragma unroll
;                 for (int t = 0; t < 4; ++t) { const f32x4 q4 = *(const LAS f32x4*)(qs + t * 64 + 4 * d4); s[t] += k4[0] * q4[0] + k4[1] * q4[1] + k4[2] * q4[2] + k4[3] * q4[3]; } } }
	v_fmac_f32_e32 v4, v210, v32
	v_fmac_f32_e32 v5, v210, v36
	v_fmac_f32_e32 v6, v210, v54
	v_fmac_f32_e32 v7, v210, v60
	v_fmac_f32_e32 v148, v214, v32
	v_fmac_f32_e32 v149, v214, v36
	v_fmac_f32_e32 v150, v214, v54
	v_fmac_f32_e32 v151, v214, v60
	v_fmac_f32_e32 v152, v218, v32
	v_fmac_f32_e32 v153, v218, v36
	v_fmac_f32_e32 v154, v218, v54
	v_fmac_f32_e32 v155, v218, v60
	v_fmac_f32_e32 v4, v211, v33
	v_fmac_f32_e32 v5, v211, v37
	v_fmac_f32_e32 v6, v211, v55
	v_fmac_f32_e32 v7, v211, v61
	v_fmac_f32_e32 v148, v215, v33
	v_fmac_f32_e32 v149, v215, v37
	v_fmac_f32_e32 v150, v215, v55
	v_fmac_f32_e32 v151, v215, v61
	v_fmac_f32_e32 v152, v219, v33
	v_fmac_f32_e32 v153, v219, v37
	v_fmac_f32_e32 v154, v219, v55
	v_fmac_f32_e32 v155, v219, v61
	v_fmac_f32_e32 v4, v212, v34
	v_fmac_f32_e32 v5, v212, v38
	v_fmac_f32_e32 v6, v212, v56
	v_fmac_f32_e32 v7, v212, v62
	v_fmac_f32_e32 v148, v216, v34
	v_fmac_f32_e32 v149, v216, v38
	v_fmac_f32_e32 v150, v216, v56
	v_fmac_f32_e32 v151, v216, v62
	v_fmac_f32_e32 v152, v220, v34
	v_fmac_f32_e32 v153, v220, v38
	v_fmac_f32_e32 v154, v220, v56
	v_fmac_f32_e32 v155, v220, v62
	v_fmac_f32_e32 v4, v213, v35
	v_fmac_f32_e32 v5, v213, v39
	v_fmac_f32_e32 v6, v213, v57
	v_fmac_f32_e32 v7, v213, v63
	v_fmac_f32_e32 v148, v217, v35
	v_fmac_f32_e32 v149, v217, v39
	v_fmac_f32_e32 v150, v217, v57
	v_fmac_f32_e32 v151, v217, v63
	v_fmac_f32_e32 v152, v221, v35
	v_fmac_f32_e32 v153, v221, v39
	v_fmac_f32_e32 v154, v221, v57
	v_fmac_f32_e32 v155, v221, v63
	global_load_dwordx4 v[210:213], v[2:3], off offset:96
	global_load_dwordx4 v[214:217], v[44:45], off offset:96
	global_load_dwordx4 v[218:221], v[48:49], off offset:96
	ds_read_b128 v[32:35], v43 offset:48
	ds_read_b128 v[36:39], v43 offset:304
	ds_read_b128 v[54:57], v43 offset:560
	ds_read_b128 v[60:63], v43 offset:816
	s_waitcnt vmcnt(18)
	s_waitcnt lgkmcnt(4)
	v_fmac_f32_e32 v4, v222, v70
	v_fmac_f32_e32 v5, v222, v74
	v_fmac_f32_e32 v6, v222, v78
	v_fmac_f32_e32 v7, v222, v82
	v_fmac_f32_e32 v148, v226, v70
	v_fmac_f32_e32 v149, v226, v74
	v_fmac_f32_e32 v150, v226, v78
	v_fmac_f32_e32 v151, v226, v82
	v_fmac_f32_e32 v152, v230, v70
	v_fmac_f32_e32 v153, v230, v74
	v_fmac_f32_e32 v154, v230, v78
	v_fmac_f32_e32 v155, v230, v82
	v_fmac_f32_e32 v4, v223, v71
	v_fmac_f32_e32 v5, v223, v75
	v_fmac_f32_e32 v6, v223, v79
	v_fmac_f32_e32 v7, v223, v83
	v_fmac_f32_e32 v148, v227, v71
	v_fmac_f32_e32 v149, v227, v75
	v_fmac_f32_e32 v150, v227, v79
	v_fmac_f32_e32 v151, v227, v83
	v_fmac_f32_e32 v152, v231, v71
	v_fmac_f32_e32 v153, v231, v75
	v_fmac_f32_e32 v154, v231, v79
	v_fmac_f32_e32 v155, v231, v83
	v_fmac_f32_e32 v4, v224, v72
	v_fmac_f32_e32 v5, v224, v76
	v_fmac_f32_e32 v6, v224, v80
	v_fmac_f32_e32 v7, v224, v84
	v_fmac_f32_e32 v148, v228, v72
	v_fmac_f32_e32 v149, v228, v76
	v_fmac_f32_e32 v150, v228, v80
	v_fmac_f32_e32 v151, v228, v84
	v_fmac_f32_e32 v152, v232, v72
	v_fmac_f32_e32 v153, v232, v76
	v_fmac_f32_e32 v154, v232, v80
	v_fmac_f32_e32 v155, v232, v84
	v_fmac_f32_e32 v4, v225, v73
	v_fmac_f32_e32 v5, v225, v77
	v_fmac_f32_e32 v6, v225, v81
	v_fmac_f32_e32 v7, v225, v85
	v_fmac_f32_e32 v148, v229, v73
	v_fmac_f32_e32 v149, v229, v77
	v_fmac_f32_e32 v150, v229, v81
	v_fmac_f32_e32 v151, v229, v85
	v_fmac_f32_e32 v152, v233, v73
	v_fmac_f32_e32 v153, v233, v77
	v_fmac_f32_e32 v154, v233, v81
	v_fmac_f32_e32 v155, v233, v85
	global_load_dwordx4 v[222:225], v[2:3], off offset:112
	global_load_dwordx4 v[226:229], v[44:45], off offset:112
	global_load_dwordx4 v[230:233], v[48:49], off offset:112
	ds_read_b128 v[70:73], v43 offset:64
	ds_read_b128 v[74:77], v43 offset:320
	ds_read_b128 v[78:81], v43 offset:576
	ds_read_b128 v[82:85], v43 offset:832
	s_waitcnt vmcnt(18)
	s_waitcnt lgkmcnt(4)
	v_fmac_f32_e32 v4, v234, v32
	v_fmac_f32_e32 v5, v234, v36
	v_fmac_f32_e32 v6, v234, v54
	v_fmac_f32_e32 v7, v234, v60
	v_fmac_f32_e32 v148, v238, v32
	v_fmac_f32_e32 v149, v238, v36
	v_fmac_f32_e32 v150, v238, v54
	v_fmac_f32_e32 v151, v238, v60
	v_fmac_f32_e32 v152, v242, v32
	v_fmac_f32_e32 v153, v242, v36
	v_fmac_f32_e32 v154, v242, v54
	v_fmac_f32_e32 v155, v242, v60
	v_fmac_f32_e32 v4, v235, v33
	v_fmac_f32_e32 v5, v235, v37
	v_fmac_f32_e32 v6, v235, v55
	v_fmac_f32_e32 v7, v235, v61
	v_fmac_f32_e32 v148, v239, v33
	v_fmac_f32_e32 v149, v239, v37
	v_fmac_f32_e32 v150, v239, v55
	v_fmac_f32_e32 v151, v239, v61
	v_fmac_f32_e32 v152, v243, v33
	v_fmac_f32_e32 v153, v243, v37
	v_fmac_f32_e32 v154, v243, v55
	v_fmac_f32_e32 v155, v243, v61
	v_fmac_f32_e32 v4, v236, v34
	v_fmac_f32_e32 v5, v236, v38
	v_fmac_f32_e32 v6, v236, v56
	v_fmac_f32_e32 v7, v236, v62
	v_fmac_f32_e32 v148, v240, v34
	v_fmac_f32_e32 v149, v240, v38
	v_fmac_f32_e32 v150, v240, v56
	v_fmac_f32_e32 v151, v240, v62
	v_fmac_f32_e32 v152, v244, v34
	v_fmac_f32_e32 v153, v244, v38
	v_fmac_f32_e32 v154, v244, v56
	v_fmac_f32_e32 v155, v244, v62
	v_fmac_f32_e32 v4, v237, v35
	v_fmac_f32_e32 v5, v237, v39
	v_fmac_f32_e32 v6, v237, v57
	v_fmac_f32_e32 v7, v237, v63
	v_fmac_f32_e32 v148, v241, v35
	v_fmac_f32_e32 v149, v241, v39
	v_fmac_f32_e32 v150, v241, v57
	v_fmac_f32_e32 v151, v241, v63
	v_fmac_f32_e32 v152, v245, v35
	v_fmac_f32_e32 v153, v245, v39
	v_fmac_f32_e32 v154, v245, v57
	v_fmac_f32_e32 v155, v245, v63
	global_load_dwordx4 v[234:237], v[2:3], off offset:128
	global_load_dwordx4 v[238:241], v[44:45], off offset:128
	global_load_dwordx4 v[242:245], v[48:49], off offset:128
	ds_read_b128 v[32:35], v43 offset:80
	ds_read_b128 v[36:39], v43 offset:336
	ds_read_b128 v[54:57], v43 offset:592
	ds_read_b128 v[60:63], v43 offset:848
	s_waitcnt vmcnt(18)
	s_waitcnt lgkmcnt(4)
; #define LAS __attribute__((address_space(3)))
; DI void attn_sample_task(LAS unsigned char* wl, int task, int l, ArgsP a, const bf16_t* Q, bf16_t* YB, int lane) {
;     ...
;     for (int rr = 0; rr < 3; ++rr) { const int j = rr * 64 + lane; float s[4] = {0.f, 0.f, 0.f, 0.f};
;         if (j < 132) { const float* kp = j < 128 ? ck + (size_t)j * 128 : nk + (size_t)(j - 128) * 128;
; #pragma unroll 4
;             for (int d4 = 0; d4 < 16; ++d4) { const f32x4 k4 = *(const f32x4*)(kp + 4 * d4);
; #pragma unroll
;                 for (int t = 0; t < 4; ++t) { const f32x4 q4 = *(const LAS f32x4*)(qs + t * 64 + 4 * d4); s[t] += k4[0] * q4[0] + k4[1] * q4[1] + k4[2] * q4[2] + k4[3] * q4[3]; } } }
	v_fmac_f32_e32 v4, v246, v70
	v_fmac_f32_e32 v5, v246, v74
	v_fmac_f32_e32 v6, v246, v78
	v_fmac_f32_e32 v7, v246, v82
	v_fmac_f32_e32 v148, v250, v70
	v_fmac_f32_e32 v149, v250, v74
	v_fmac_f32_e32 v150, v250, v78
	v_fmac_f32_e32 v151, v250, v82
	v_fmac_f32_e32 v152, v182, v70
	v_fmac_f32_e32 v153, v182, v74
	v_fmac_f32_e32 v154, v182, v78
	v_fmac_f32_e32 v155, v182, v82
	v_fmac_f32_e32 v4, v247, v71
	v_fmac_f32_e32 v5, v247, v75
	v_fmac_f32_e32 v6, v247, v79
	v_fmac_f32_e32 v7, v247, v83
	v_fmac_f32_e32 v148, v251, v71
	v_fmac_f32_e32 v149, v251, v75
	v_fmac_f32_e32 v150, v251, v79
	v_fmac_f32_e32 v151, v251, v83
	v_fmac_f32_e32 v152, v183, v71
	v_fmac_f32_e32 v153, v183, v75
	v_fmac_f32_e32 v154, v183, v79
	v_fmac_f32_e32 v155, v183, v83
	v_fmac_f32_e32 v4, v248, v72
	v_fmac_f32_e32 v5, v248, v76
	v_fmac_f32_e32 v6, v248, v80
	v_fmac_f32_e32 v7, v248, v84
	v_fmac_f32_e32 v148, v252, v72
	v_fmac_f32_e32 v149, v252, v76
	v_fmac_f32_e32 v150, v252, v80
	v_fmac_f32_e32 v151, v252, v84
	v_fmac_f32_e32 v152, v184, v72
	v_fmac_f32_e32 v153, v184, v76
	v_fmac_f32_e32 v154, v184, v80
	v_fmac_f32_e32 v155, v184, v84
	v_fmac_f32_e32 v4, v249, v73
	v_fmac_f32_e32 v5, v249, v77
	v_fmac_f32_e32 v6, v249, v81
	v_fmac_f32_e32 v7, v249, v85
	v_fmac_f32_e32 v148, v253, v73
	v_fmac_f32_e32 v149, v253, v77
	v_fmac_f32_e32 v150, v253, v81
	v_fmac_f32_e32 v151, v253, v85
	v_fmac_f32_e32 v152, v185, v73
	v_fmac_f32_e32 v153, v185, v77
	v_fmac_f32_e32 v154, v185, v81
	v_fmac_f32_e32 v155, v185, v85
	global_load_dwordx4 v[246:249], v[2:3], off offset:144
	global_load_dwordx4 v[250:253], v[44:45], off offset:144
	global_load_dwordx4 v[182:185], v[48:49], off offset:144
	ds_read_b128 v[70:73], v43 offset:96
	ds_read_b128 v[74:77], v43 offset:352
	ds_read_b128 v[78:81], v43 offset:608
	ds_read_b128 v[82:85], v43 offset:864
	s_waitcnt vmcnt(18)
	s_waitcnt lgkmcnt(4)
	v_fmac_f32_e32 v4, v186, v32
	v_fmac_f32_e32 v5, v186, v36
	v_fmac_f32_e32 v6, v186, v54
	v_fmac_f32_e32 v7, v186, v60
	v_fmac_f32_e32 v148, v190, v32
	v_fmac_f32_e32 v149, v190, v36
	v_fmac_f32_e32 v150, v190, v54
	v_fmac_f32_e32 v151, v190, v60
	v_fmac_f32_e32 v152, v156, v32
	v_fmac_f32_e32 v153, v156, v36
	v_fmac_f32_e32 v154, v156, v54
	v_fmac_f32_e32 v155, v156, v60
	v_fmac_f32_e32 v4, v187, v33
	v_fmac_f32_e32 v5, v187, v37
	v_fmac_f32_e32 v6, v187, v55
	v_fmac_f32_e32 v7, v187, v61
	v_fmac_f32_e32 v148, v191, v33
	v_fmac_f32_e32 v149, v191, v37
	v_fmac_f32_e32 v150, v191, v55
	v_fmac_f32_e32 v151, v191, v61
	v_fmac_f32_e32 v152, v157, v33
	v_fmac_f32_e32 v153, v157, v37
	v_fmac_f32_e32 v154, v157, v55
	v_fmac_f32_e32 v155, v157, v61
	v_fmac_f32_e32 v4, v188, v34
	v_fmac_f32_e32 v5, v188, v38
	v_fmac_f32_e32 v6, v188, v56
	v_fmac_f32_e32 v7, v188, v62
	v_fmac_f32_e32 v148, v192, v34
	v_fmac_f32_e32 v149, v192, v38
	v_fmac_f32_e32 v150, v192, v56
	v_fmac_f32_e32 v151, v192, v62
	v_fmac_f32_e32 v152, v158, v34
	v_fmac_f32_e32 v153, v158, v38
	v_fmac_f32_e32 v154, v158, v56
	v_fmac_f32_e32 v155, v158, v62
	v_fmac_f32_e32 v4, v189, v35
	v_fmac_f32_e32 v5, v189, v39
	v_fmac_f32_e32 v6, v189, v57
	v_fmac_f32_e32 v7, v189, v63
	v_fmac_f32_e32 v148, v193, v35
	v_fmac_f32_e32 v149, v193, v39
	v_fmac_f32_e32 v150, v193, v57
	v_fmac_f32_e32 v151, v193, v63
	v_fmac_f32_e32 v152, v159, v35
	v_fmac_f32_e32 v153, v159, v39
	v_fmac_f32_e32 v154, v159, v57
	v_fmac_f32_e32 v155, v159, v63
	global_load_dwordx4 v[186:189], v[2:3], off offset:160
	global_load_dwordx4 v[190:193], v[44:45], off offset:160
	global_load_dwordx4 v[156:159], v[48:49], off offset:160
	ds_read_b128 v[32:35], v43 offset:112
	ds_read_b128 v[36:39], v43 offset:368
	ds_read_b128 v[54:57], v43 offset:624
	ds_read_b128 v[60:63], v43 offset:880
	s_waitcnt vmcnt(18)
	s_waitcnt lgkmcnt(4)
	v_fmac_f32_e32 v4, v160, v70
	v_fmac_f32_e32 v5, v160, v74
	v_fmac_f32_e32 v6, v160, v78
	v_fmac_f32_e32 v7, v160, v82
	v_fmac_f32_e32 v148, v170, v70
	v_fmac_f32_e32 v149, v170, v74
	v_fmac_f32_e32 v150, v170, v78
	v_fmac_f32_e32 v151, v170, v82
	v_fmac_f32_e32 v152, v174, v70
	v_fmac_f32_e32 v153, v174, v74
	v_fmac_f32_e32 v154, v174, v78
	v_fmac_f32_e32 v155, v174, v82
	v_fmac_f32_e32 v4, v161, v71
	v_fmac_f32_e32 v5, v161, v75
	v_fmac_f32_e32 v6, v161, v79
	v_fmac_f32_e32 v7, v161, v83
	v_fmac_f32_e32 v148, v171, v71
	v_fmac_f32_e32 v149, v171, v75
	v_fmac_f32_e32 v150, v171, v79
	v_fmac_f32_e32 v151, v171, v83
	v_fmac_f32_e32 v152, v175, v71
	v_fmac_f32_e32 v153, v175, v75
	v_fmac_f32_e32 v154, v175, v79
	v_fmac_f32_e32 v155, v175, v83
	v_fmac_f32_e32 v4, v162, v72
	v_fmac_f32_e32 v5, v162, v76
	v_fmac_f32_e32 v6, v162, v80
	v_fmac_f32_e32 v7, v162, v84
	v_fmac_f32_e32 v148, v172, v72
	v_fmac_f32_e32 v149, v172, v76
	v_fmac_f32_e32 v150, v172, v80
	v_fmac_f32_e32 v151, v172, v84
	v_fmac_f32_e32 v152, v176, v72
	v_fmac_f32_e32 v153, v176, v76
	v_fmac_f32_e32 v154, v176, v80
	v_fmac_f32_e32 v155, v176, v84
	v_fmac_f32_e32 v4, v163, v73
	v_fmac_f32_e32 v5, v163, v77
	v_fmac_f32_e32 v6, v163, v81
	v_fmac_f32_e32 v7, v163, v85
	v_fmac_f32_e32 v148, v173, v73
	v_fmac_f32_e32 v149, v173, v77
	v_fmac_f32_e32 v150, v173, v81
	v_fmac_f32_e32 v151, v173, v85
	v_fmac_f32_e32 v152, v177, v73
	v_fmac_f32_e32 v153, v177, v77
	v_fmac_f32_e32 v154, v177, v81
	v_fmac_f32_e32 v155, v177, v85
	global_load_dwordx4 v[160:163], v[2:3], off offset:176
	global_load_dwordx4 v[170:173], v[44:45], off offset:176
	global_load_dwordx4 v[174:177], v[48:49], off offset:176
	ds_read_b128 v[70:73], v43 offset:128
	ds_read_b128 v[74:77], v43 offset:384
	ds_read_b128 v[78:81], v43 offset:640
	ds_read_b128 v[82:85], v43 offset:896
	s_waitcnt vmcnt(18)
	s_waitcnt lgkmcnt(4)
; #define LAS __attribute__((address_space(3)))
; DI void attn_sample_task(LAS unsigned char* wl, int task, int l, ArgsP a, const bf16_t* Q, bf16_t* YB, int lane) {
;     ...
;     for (int rr = 0; rr < 3; ++rr) { const int j = rr * 64 + lane; float s[4] = {0.f, 0.f, 0.f, 0.f};
;         if (j < 132) { const float* kp = j < 128 ? ck + (size_t)j * 128 : nk + (size_t)(j - 128) * 128;
; #pragma unroll 4
;             for (int d4 = 0; d4 < 16; ++d4) { const f32x4 k4 = *(const f32x4*)(kp + 4 * d4);
; #pragma unroll
;                 for (int t = 0; t < 4; ++t) { const f32x4 q4 = *(const LAS f32x4*)(qs + t * 64 + 4 * d4); s[t] += k4[0] * q4[0] + k4[1] * q4[1] + k4[2] * q4[2] + k4[3] * q4[3]; } } }
	v_fmac_f32_e32 v4, v198, v32
	v_fmac_f32_e32 v5, v198, v36
	v_fmac_f32_e32 v6, v198, v54
	v_fmac_f32_e32 v7, v198, v60
	v_fmac_f32_e32 v148, v202, v32
	v_fmac_f32_e32 v149, v202, v36
	v_fmac_f32_e32 v150, v202, v54
	v_fmac_f32_e32 v151, v202, v60
	v_fmac_f32_e32 v152, v206, v32
	v_fmac_f32_e32 v153, v206, v36
	v_fmac_f32_e32 v154, v206, v54
	v_fmac_f32_e32 v155, v206, v60
	v_fmac_f32_e32 v4, v199, v33
	v_fmac_f32_e32 v5, v199, v37
	v_fmac_f32_e32 v6, v199, v55
	v_fmac_f32_e32 v7, v199, v61
	v_fmac_f32_e32 v148, v203, v33
	v_fmac_f32_e32 v149, v203, v37
	v_fmac_f32_e32 v150, v203, v55
	v_fmac_f32_e32 v151, v203, v61
	v_fmac_f32_e32 v152, v207, v33
	v_fmac_f32_e32 v153, v207, v37
	v_fmac_f32_e32 v154, v207, v55
	v_fmac_f32_e32 v155, v207, v61
	v_fmac_f32_e32 v4, v200, v34
	v_fmac_f32_e32 v5, v200, v38
	v_fmac_f32_e32 v6, v200, v56
	v_fmac_f32_e32 v7, v200, v62
	v_fmac_f32_e32 v148, v204, v34
	v_fmac_f32_e32 v149, v204, v38
	v_fmac_f32_e32 v150, v204, v56
	v_fmac_f32_e32 v151, v204, v62
	v_fmac_f32_e32 v152, v208, v34
	v_fmac_f32_e32 v153, v208, v38
	v_fmac_f32_e32 v154, v208, v56
	v_fmac_f32_e32 v155, v208, v62
	v_fmac_f32_e32 v4, v201, v35
	v_fmac_f32_e32 v5, v201, v39
	v_fmac_f32_e32 v6, v201, v57
	v_fmac_f32_e32 v7, v201, v63
	v_fmac_f32_e32 v148, v205, v35
	v_fmac_f32_e32 v149, v205, v39
	v_fmac_f32_e32 v150, v205, v57
	v_fmac_f32_e32 v151, v205, v63
	v_fmac_f32_e32 v152, v209, v35
	v_fmac_f32_e32 v153, v209, v39
	v_fmac_f32_e32 v154, v209, v57
	v_fmac_f32_e32 v155, v209, v63
	global_load_dwordx4 v[198:201], v[2:3], off offset:192
	global_load_dwordx4 v[202:205], v[44:45], off offset:192
	global_load_dwordx4 v[206:209], v[48:49], off offset:192
	ds_read_b128 v[32:35], v43 offset:144
	ds_read_b128 v[36:39], v43 offset:400
	ds_read_b128 v[54:57], v43 offset:656
	ds_read_b128 v[60:63], v43 offset:912
	s_waitcnt vmcnt(18)
	s_waitcnt lgkmcnt(4)
	v_fmac_f32_e32 v4, v210, v70
	v_fmac_f32_e32 v5, v210, v74
	v_fmac_f32_e32 v6, v210, v78
	v_fmac_f32_e32 v7, v210, v82
	v_fmac_f32_e32 v148, v214, v70
	v_fmac_f32_e32 v149, v214, v74
	v_fmac_f32_e32 v150, v214, v78
	v_fmac_f32_e32 v151, v214, v82
	v_fmac_f32_e32 v152, v218, v70
	v_fmac_f32_e32 v153, v218, v74
	v_fmac_f32_e32 v154, v218, v78
	v_fmac_f32_e32 v155, v218, v82
	v_fmac_f32_e32 v4, v211, v71
	v_fmac_f32_e32 v5, v211, v75
	v_fmac_f32_e32 v6, v211, v79
	v_fmac_f32_e32 v7, v211, v83
	v_fmac_f32_e32 v148, v215, v71
	v_fmac_f32_e32 v149, v215, v75
	v_fmac_f32_e32 v150, v215, v79
	v_fmac_f32_e32 v151, v215, v83
	v_fmac_f32_e32 v152, v219, v71
	v_fmac_f32_e32 v153, v219, v75
	v_fmac_f32_e32 v154, v219, v79
	v_fmac_f32_e32 v155, v219, v83
	v_fmac_f32_e32 v4, v212, v72
	v_fmac_f32_e32 v5, v212, v76
	v_fmac_f32_e32 v6, v212, v80
	v_fmac_f32_e32 v7, v212, v84
	v_fmac_f32_e32 v148, v216, v72
	v_fmac_f32_e32 v149, v216, v76
	v_fmac_f32_e32 v150, v216, v80
	v_fmac_f32_e32 v151, v216, v84
	v_fmac_f32_e32 v152, v220, v72
	v_fmac_f32_e32 v153, v220, v76
	v_fmac_f32_e32 v154, v220, v80
	v_fmac_f32_e32 v155, v220, v84
	v_fmac_f32_e32 v4, v213, v73
	v_fmac_f32_e32 v5, v213, v77
	v_fmac_f32_e32 v6, v213, v81
	v_fmac_f32_e32 v7, v213, v85
	v_fmac_f32_e32 v148, v217, v73
	v_fmac_f32_e32 v149, v217, v77
	v_fmac_f32_e32 v150, v217, v81
	v_fmac_f32_e32 v151, v217, v85
	v_fmac_f32_e32 v152, v221, v73
	v_fmac_f32_e32 v153, v221, v77
	v_fmac_f32_e32 v154, v221, v81
	v_fmac_f32_e32 v155, v221, v85
	global_load_dwordx4 v[210:213], v[2:3], off offset:208
	global_load_dwordx4 v[214:217], v[44:45], off offset:208
	global_load_dwordx4 v[218:221], v[48:49], off offset:208
	ds_read_b128 v[70:73], v43 offset:160
	ds_read_b128 v[74:77], v43 offset:416
	ds_read_b128 v[78:81], v43 offset:672
	ds_read_b128 v[82:85], v43 offset:928
	s_waitcnt vmcnt(18)
	s_waitcnt lgkmcnt(4)
	v_fmac_f32_e32 v4, v222, v32
	v_fmac_f32_e32 v5, v222, v36
	v_fmac_f32_e32 v6, v222, v54
	v_fmac_f32_e32 v7, v222, v60
	v_fmac_f32_e32 v148, v226, v32
	v_fmac_f32_e32 v149, v226, v36
	v_fmac_f32_e32 v150, v226, v54
	v_fmac_f32_e32 v151, v226, v60
	v_fmac_f32_e32 v152, v230, v32
	v_fmac_f32_e32 v153, v230, v36
	v_fmac_f32_e32 v154, v230, v54
	v_fmac_f32_e32 v155, v230, v60
	v_fmac_f32_e32 v4, v223, v33
	v_fmac_f32_e32 v5, v223, v37
	v_fmac_f32_e32 v6, v223, v55
	v_fmac_f32_e32 v7, v223, v61
	v_fmac_f32_e32 v148, v227, v33
	v_fmac_f32_e32 v149, v227, v37
	v_fmac_f32_e32 v150, v227, v55
	v_fmac_f32_e32 v151, v227, v61
	v_fmac_f32_e32 v152, v231, v33
	v_fmac_f32_e32 v153, v231, v37
	v_fmac_f32_e32 v154, v231, v55
	v_fmac_f32_e32 v155, v231, v61
	v_fmac_f32_e32 v4, v224, v34
	v_fmac_f32_e32 v5, v224, v38
	v_fmac_f32_e32 v6, v224, v56
	v_fmac_f32_e32 v7, v224, v62
	v_fmac_f32_e32 v148, v228, v34
	v_fmac_f32_e32 v149, v228, v38
	v_fmac_f32_e32 v150, v228, v56
	v_fmac_f32_e32 v151, v228, v62
	v_fmac_f32_e32 v152, v232, v34
	v_fmac_f32_e32 v153, v232, v38
	v_fmac_f32_e32 v154, v232, v56
	v_fmac_f32_e32 v155, v232, v62
	v_fmac_f32_e32 v4, v225, v35
	v_fmac_f32_e32 v5, v225, v39
	v_fmac_f32_e32 v6, v225, v57
	v_fmac_f32_e32 v7, v225, v63
	v_fmac_f32_e32 v148, v229, v35
	v_fmac_f32_e32 v149, v229, v39
	v_fmac_f32_e32 v150, v229, v57
	v_fmac_f32_e32 v151, v229, v63
	v_fmac_f32_e32 v152, v233, v35
	v_fmac_f32_e32 v153, v233, v39
	v_fmac_f32_e32 v154, v233, v57
	v_fmac_f32_e32 v155, v233, v63
	ds_read_b128 v[32:35], v43 offset:176
	ds_read_b128 v[36:39], v43 offset:432
	ds_read_b128 v[54:57], v43 offset:688
	ds_read_b128 v[60:63], v43 offset:944
	s_waitcnt vmcnt(15)
	s_waitcnt lgkmcnt(4)
; #define LAS __attribute__((address_space(3)))
; DI void attn_sample_task(LAS unsigned char* wl, int task, int l, ArgsP a, const bf16_t* Q, bf16_t* YB, int lane) {
;     ...
;     for (int rr = 0; rr < 3; ++rr) { const int j = rr * 64 + lane; float s[4] = {0.f, 0.f, 0.f, 0.f};
;         if (j < 132) { const float* kp = j < 128 ? ck + (size_t)j * 128 : nk + (size_t)(j - 128) * 128;
; #pragma unroll 4
;             for (int d4 = 0; d4 < 16; ++d4) { const f32x4 k4 = *(const f32x4*)(kp + 4 * d4);
; #pragma unroll
;                 for (int t = 0; t < 4; ++t) { const f32x4 q4 = *(const LAS f32x4*)(qs + t * 64 + 4 * d4); s[t] += k4[0] * q4[0] + k4[1] * q4[1] + k4[2] * q4[2] + k4[3] * q4[3]; } } }
	v_fmac_f32_e32 v4, v234, v70
	v_fmac_f32_e32 v5, v234, v74
	v_fmac_f32_e32 v6, v234, v78
	v_fmac_f32_e32 v7, v234, v82
	v_fmac_f32_e32 v148, v238, v70
	v_fmac_f32_e32 v149, v238, v74
	v_fmac_f32_e32 v150, v238, v78
	v_fmac_f32_e32 v151, v238, v82
	v_fmac_f32_e32 v152, v242, v70
	v_fmac_f32_e32 v153, v242, v74
	v_fmac_f32_e32 v154, v242, v78
	v_fmac_f32_e32 v155, v242, v82
	v_fmac_f32_e32 v4, v235, v71
	v_fmac_f32_e32 v5, v235, v75
	v_fmac_f32_e32 v6, v235, v79
	v_fmac_f32_e32 v7, v235, v83
	v_fmac_f32_e32 v148, v239, v71
	v_fmac_f32_e32 v149, v239, v75
	v_fmac_f32_e32 v150, v239, v79
	v_fmac_f32_e32 v151, v239, v83
	v_fmac_f32_e32 v152, v243, v71
	v_fmac_f32_e32 v153, v243, v75
	v_fmac_f32_e32 v154, v243, v79
	v_fmac_f32_e32 v155, v243, v83
	v_fmac_f32_e32 v4, v236, v72
	v_fmac_f32_e32 v5, v236, v76
	v_fmac_f32_e32 v6, v236, v80
	v_fmac_f32_e32 v7, v236, v84
	v_fmac_f32_e32 v148, v240, v72
	v_fmac_f32_e32 v149, v240, v76
	v_fmac_f32_e32 v150, v240, v80
	v_fmac_f32_e32 v151, v240, v84
	v_fmac_f32_e32 v152, v244, v72
	v_fmac_f32_e32 v153, v244, v76
	v_fmac_f32_e32 v154, v244, v80
	v_fmac_f32_e32 v155, v244, v84
	v_fmac_f32_e32 v4, v237, v73
	v_fmac_f32_e32 v5, v237, v77
	v_fmac_f32_e32 v6, v237, v81
	v_fmac_f32_e32 v7, v237, v85
	v_fmac_f32_e32 v148, v241, v73
	v_fmac_f32_e32 v149, v241, v77
	v_fmac_f32_e32 v150, v241, v81
	v_fmac_f32_e32 v151, v241, v85
	v_fmac_f32_e32 v152, v245, v73
	v_fmac_f32_e32 v153, v245, v77
	v_fmac_f32_e32 v154, v245, v81
	v_fmac_f32_e32 v155, v245, v85
	ds_read_b128 v[70:73], v43 offset:192
	ds_read_b128 v[74:77], v43 offset:448
	ds_read_b128 v[78:81], v43 offset:704
	ds_read_b128 v[82:85], v43 offset:960
	s_waitcnt vmcnt(12)
	s_waitcnt lgkmcnt(4)
	v_fmac_f32_e32 v4, v246, v32
	v_fmac_f32_e32 v5, v246, v36
	v_fmac_f32_e32 v6, v246, v54
	v_fmac_f32_e32 v7, v246, v60
	v_fmac_f32_e32 v148, v250, v32
	v_fmac_f32_e32 v149, v250, v36
	v_fmac_f32_e32 v150, v250, v54
	v_fmac_f32_e32 v151, v250, v60
	v_fmac_f32_e32 v152, v182, v32
	v_fmac_f32_e32 v153, v182, v36
	v_fmac_f32_e32 v154, v182, v54
	v_fmac_f32_e32 v155, v182, v60
	v_fmac_f32_e32 v4, v247, v33
	v_fmac_f32_e32 v5, v247, v37
	v_fmac_f32_e32 v6, v247, v55
	v_fmac_f32_e32 v7, v247, v61
	v_fmac_f32_e32 v148, v251, v33
	v_fmac_f32_e32 v149, v251, v37
	v_fmac_f32_e32 v150, v251, v55
	v_fmac_f32_e32 v151, v251, v61
	v_fmac_f32_e32 v152, v183, v33
	v_fmac_f32_e32 v153, v183, v37
	v_fmac_f32_e32 v154, v183, v55
	v_fmac_f32_e32 v155, v183, v61
	v_fmac_f32_e32 v4, v248, v34
	v_fmac_f32_e32 v5, v248, v38
	v_fmac_f32_e32 v6, v248, v56
	v_fmac_f32_e32 v7, v248, v62
	v_fmac_f32_e32 v148, v252, v34
	v_fmac_f32_e32 v149, v252, v38
	v_fmac_f32_e32 v150, v252, v56
	v_fmac_f32_e32 v151, v252, v62
	v_fmac_f32_e32 v152, v184, v34
	v_fmac_f32_e32 v153, v184, v38
	v_fmac_f32_e32 v154, v184, v56
	v_fmac_f32_e32 v155, v184, v62
	v_fmac_f32_e32 v4, v249, v35
	v_fmac_f32_e32 v5, v249, v39
	v_fmac_f32_e32 v6, v249, v57
	v_fmac_f32_e32 v7, v249, v63
	v_fmac_f32_e32 v148, v253, v35
	v_fmac_f32_e32 v149, v253, v39
	v_fmac_f32_e32 v150, v253, v57
	v_fmac_f32_e32 v151, v253, v63
	v_fmac_f32_e32 v152, v185, v35
	v_fmac_f32_e32 v153, v185, v39
	v_fmac_f32_e32 v154, v185, v57
	v_fmac_f32_e32 v155, v185, v63
	ds_read_b128 v[32:35], v43 offset:208
	ds_read_b128 v[36:39], v43 offset:464
	ds_read_b128 v[54:57], v43 offset:720
	ds_read_b128 v[60:63], v43 offset:976
	s_waitcnt vmcnt(9)
	s_waitcnt lgkmcnt(4)
	v_fmac_f32_e32 v4, v186, v70
	v_fmac_f32_e32 v5, v186, v74
	v_fmac_f32_e32 v6, v186, v78
	v_fmac_f32_e32 v7, v186, v82
	v_fmac_f32_e32 v148, v190, v70
	v_fmac_f32_e32 v149, v190, v74
	v_fmac_f32_e32 v150, v190, v78
	v_fmac_f32_e32 v151, v190, v82
	v_fmac_f32_e32 v152, v156, v70
	v_fmac_f32_e32 v153, v156, v74
	v_fmac_f32_e32 v154, v156, v78
	v_fmac_f32_e32 v155, v156, v82
	v_fmac_f32_e32 v4, v187, v71
	v_fmac_f32_e32 v5, v187, v75
	v_fmac_f32_e32 v6, v187, v79
	v_fmac_f32_e32 v7, v187, v83
	v_fmac_f32_e32 v148, v191, v71
	v_fmac_f32_e32 v149, v191, v75
	v_fmac_f32_e32 v150, v191, v79
	v_fmac_f32_e32 v151, v191, v83
	v_fmac_f32_e32 v152, v157, v71
	v_fmac_f32_e32 v153, v157, v75
	v_fmac_f32_e32 v154, v157, v79
	v_fmac_f32_e32 v155, v157, v83
	v_fmac_f32_e32 v4, v188, v72
	v_fmac_f32_e32 v5, v188, v76
	v_fmac_f32_e32 v6, v188, v80
	v_fmac_f32_e32 v7, v188, v84
	v_fmac_f32_e32 v148, v192, v72
	v_fmac_f32_e32 v149, v192, v76
	v_fmac_f32_e32 v150, v192, v80
	v_fmac_f32_e32 v151, v192, v84
	v_fmac_f32_e32 v152, v158, v72
	v_fmac_f32_e32 v153, v158, v76
	v_fmac_f32_e32 v154, v158, v80
	v_fmac_f32_e32 v155, v158, v84
	v_fmac_f32_e32 v4, v189, v73
	v_fmac_f32_e32 v5, v189, v77
	v_fmac_f32_e32 v6, v189, v81
	v_fmac_f32_e32 v7, v189, v85
	v_fmac_f32_e32 v148, v193, v73
	v_fmac_f32_e32 v149, v193, v77
	v_fmac_f32_e32 v150, v193, v81
	v_fmac_f32_e32 v151, v193, v85
	v_fmac_f32_e32 v152, v159, v73
	v_fmac_f32_e32 v153, v159, v77
	v_fmac_f32_e32 v154, v159, v81
	v_fmac_f32_e32 v155, v159, v85
	ds_read_b128 v[70:73], v43 offset:224
	ds_read_b128 v[74:77], v43 offset:480
	ds_read_b128 v[78:81], v43 offset:736
	ds_read_b128 v[82:85], v43 offset:992
	s_waitcnt vmcnt(6)
	s_waitcnt lgkmcnt(4)
; #define LAS __attribute__((address_space(3)))
; DI void attn_sample_task(LAS unsigned char* wl, int task, int l, ArgsP a, const bf16_t* Q, bf16_t* YB, int lane) {
;     ...
;     for (int rr = 0; rr < 3; ++rr) { const int j = rr * 64 + lane; float s[4] = {0.f, 0.f, 0.f, 0.f};
;         if (j < 132) { const float* kp = j < 128 ? ck + (size_t)j * 128 : nk + (size_t)(j - 128) * 128;
; #pragma unroll 4
;             for (int d4 = 0; d4 < 16; ++d4) { const f32x4 k4 = *(const f32x4*)(kp + 4 * d4);
; #pragma unroll
;                 for (int t = 0; t < 4; ++t) { const f32x4 q4 = *(const LAS f32x4*)(qs + t * 64 + 4 * d4); s[t] += k4[0] * q4[0] + k4[1] * q4[1] + k4[2] * q4[2] + k4[3] * q4[3]; } } }
; #pragma unroll
;         for (int t = 0; t < 4; ++t) { const bool valid = (j < 132) && (j >= t + 1) && (j <= t + 128); const float v = valid ? s[t] * 0.125f : -INFINITY;
;             if (j < 136) ps[t * 136 + j] = v; mx[t] = fmaxf(mx[t], v); } }
	v_fmac_f32_e32 v4, v160, v32
	v_fmac_f32_e32 v5, v160, v36
	v_fmac_f32_e32 v6, v160, v54
	v_fmac_f32_e32 v7, v160, v60
	v_fmac_f32_e32 v148, v170, v32
	v_fmac_f32_e32 v149, v170, v36
	v_fmac_f32_e32 v150, v170, v54
	v_fmac_f32_e32 v151, v170, v60
	v_fmac_f32_e32 v152, v174, v32
	v_fmac_f32_e32 v153, v174, v36
	v_fmac_f32_e32 v154, v174, v54
	v_fmac_f32_e32 v155, v174, v60
	v_fmac_f32_e32 v4, v161, v33
	v_fmac_f32_e32 v5, v161, v37
	v_fmac_f32_e32 v6, v161, v55
	v_fmac_f32_e32 v7, v161, v61
	v_fmac_f32_e32 v148, v171, v33
	v_fmac_f32_e32 v149, v171, v37
	v_fmac_f32_e32 v150, v171, v55
	v_fmac_f32_e32 v151, v171, v61
	v_fmac_f32_e32 v152, v175, v33
	v_fmac_f32_e32 v153, v175, v37
	v_fmac_f32_e32 v154, v175, v55
	v_fmac_f32_e32 v155, v175, v61
	v_fmac_f32_e32 v4, v162, v34
	v_fmac_f32_e32 v5, v162, v38
	v_fmac_f32_e32 v6, v162, v56
	v_fmac_f32_e32 v7, v162, v62
	v_fmac_f32_e32 v148, v172, v34
	v_fmac_f32_e32 v149, v172, v38
	v_fmac_f32_e32 v150, v172, v56
	v_fmac_f32_e32 v151, v172, v62
	v_fmac_f32_e32 v152, v176, v34
	v_fmac_f32_e32 v153, v176, v38
	v_fmac_f32_e32 v154, v176, v56
	v_fmac_f32_e32 v155, v176, v62
	v_fmac_f32_e32 v4, v163, v35
	v_fmac_f32_e32 v5, v163, v39
	v_fmac_f32_e32 v6, v163, v57
	v_fmac_f32_e32 v7, v163, v63
	v_fmac_f32_e32 v148, v173, v35
	v_fmac_f32_e32 v149, v173, v39
	v_fmac_f32_e32 v150, v173, v57
	v_fmac_f32_e32 v151, v173, v63
	v_fmac_f32_e32 v152, v177, v35
	v_fmac_f32_e32 v153, v177, v39
	v_fmac_f32_e32 v154, v177, v57
	v_fmac_f32_e32 v155, v177, v63
	ds_read_b128 v[32:35], v43 offset:240
	ds_read_b128 v[36:39], v43 offset:496
	ds_read_b128 v[54:57], v43 offset:752
	ds_read_b128 v[60:63], v43 offset:1008
	s_waitcnt vmcnt(3)
	s_waitcnt lgkmcnt(4)
	v_fmac_f32_e32 v4, v198, v70
	v_fmac_f32_e32 v5, v198, v74
	v_fmac_f32_e32 v6, v198, v78
	v_fmac_f32_e32 v7, v198, v82
	v_fmac_f32_e32 v148, v202, v70
	v_fmac_f32_e32 v149, v202, v74
	v_fmac_f32_e32 v150, v202, v78
	v_fmac_f32_e32 v151, v202, v82
	v_fmac_f32_e32 v152, v206, v70
	v_fmac_f32_e32 v153, v206, v74
	v_fmac_f32_e32 v154, v206, v78
	v_fmac_f32_e32 v155, v206, v82
	v_fmac_f32_e32 v4, v199, v71
	v_fmac_f32_e32 v5, v199, v75
	v_fmac_f32_e32 v6, v199, v79
	v_fmac_f32_e32 v7, v199, v83
	v_fmac_f32_e32 v148, v203, v71
	v_fmac_f32_e32 v149, v203, v75
	v_fmac_f32_e32 v150, v203, v79
	v_fmac_f32_e32 v151, v203, v83
	v_fmac_f32_e32 v152, v207, v71
	v_fmac_f32_e32 v153, v207, v75
	v_fmac_f32_e32 v154, v207, v79
	v_fmac_f32_e32 v155, v207, v83
	v_fmac_f32_e32 v4, v200, v72
	v_fmac_f32_e32 v5, v200, v76
	v_fmac_f32_e32 v6, v200, v80
	v_fmac_f32_e32 v7, v200, v84
	v_fmac_f32_e32 v148, v204, v72
	v_fmac_f32_e32 v149, v204, v76
	v_fmac_f32_e32 v150, v204, v80
	v_fmac_f32_e32 v151, v204, v84
	v_fmac_f32_e32 v152, v208, v72
	v_fmac_f32_e32 v153, v208, v76
	v_fmac_f32_e32 v154, v208, v80
	v_fmac_f32_e32 v155, v208, v84
	v_fmac_f32_e32 v4, v201, v73
	v_fmac_f32_e32 v5, v201, v77
	v_fmac_f32_e32 v6, v201, v81
	v_fmac_f32_e32 v7, v201, v85
	v_fmac_f32_e32 v148, v205, v73
	v_fmac_f32_e32 v149, v205, v77
	v_fmac_f32_e32 v150, v205, v81
	v_fmac_f32_e32 v151, v205, v85
	v_fmac_f32_e32 v152, v209, v73
	v_fmac_f32_e32 v153, v209, v77
	v_fmac_f32_e32 v154, v209, v81
	v_fmac_f32_e32 v155, v209, v85
	s_waitcnt vmcnt(0)
	s_waitcnt lgkmcnt(0)
	v_fmac_f32_e32 v4, v210, v32
	v_fmac_f32_e32 v5, v210, v36
	v_fmac_f32_e32 v6, v210, v54
	v_fmac_f32_e32 v7, v210, v60
	v_fmac_f32_e32 v148, v214, v32
	v_fmac_f32_e32 v149, v214, v36
	v_fmac_f32_e32 v150, v214, v54
	v_fmac_f32_e32 v151, v214, v60
	v_fmac_f32_e32 v152, v218, v32
	v_fmac_f32_e32 v153, v218, v36
	v_fmac_f32_e32 v154, v218, v54
	v_fmac_f32_e32 v155, v218, v60
	v_fmac_f32_e32 v4, v211, v33
	v_fmac_f32_e32 v5, v211, v37
	v_fmac_f32_e32 v6, v211, v55
	v_fmac_f32_e32 v7, v211, v61
	v_fmac_f32_e32 v148, v215, v33
	v_fmac_f32_e32 v149, v215, v37
	v_fmac_f32_e32 v150, v215, v55
	v_fmac_f32_e32 v151, v215, v61
	v_fmac_f32_e32 v152, v219, v33
	v_fmac_f32_e32 v153, v219, v37
	v_fmac_f32_e32 v154, v219, v55
	v_fmac_f32_e32 v155, v219, v61
	v_fmac_f32_e32 v4, v212, v34
	v_fmac_f32_e32 v5, v212, v38
	v_fmac_f32_e32 v6, v212, v56
	v_fmac_f32_e32 v7, v212, v62
	v_fmac_f32_e32 v148, v216, v34
	v_fmac_f32_e32 v149, v216, v38
	v_fmac_f32_e32 v150, v216, v56
	v_fmac_f32_e32 v151, v216, v62
	v_fmac_f32_e32 v152, v220, v34
	v_fmac_f32_e32 v153, v220, v38
	v_fmac_f32_e32 v154, v220, v56
	v_fmac_f32_e32 v155, v220, v62
	v_fmac_f32_e32 v4, v213, v35
	v_fmac_f32_e32 v5, v213, v39
	v_fmac_f32_e32 v6, v213, v57
	v_fmac_f32_e32 v7, v213, v63
	v_fmac_f32_e32 v148, v217, v35
	v_fmac_f32_e32 v149, v217, v39
	v_fmac_f32_e32 v150, v217, v57
	v_fmac_f32_e32 v151, v217, v63
	v_fmac_f32_e32 v152, v221, v35
	v_fmac_f32_e32 v153, v221, v39
	v_fmac_f32_e32 v154, v221, v57
	v_fmac_f32_e32 v155, v221, v63
	v_mul_f32_e32 v2, 0x3e000000, v4
	v_cndmask_b32_e64 v35, v2, v195, s[6:7]
	v_mul_f32_e32 v2, 0x3e000000, v5
	v_cndmask_b32_e64 v34, v195, v2, s[8:9]
	v_mul_f32_e32 v2, 0x3e000000, v6
	v_cndmask_b32_e64 v33, v195, v2, s[10:11]
	v_mul_f32_e32 v2, 0x3e000000, v7
	v_add_u32_e32 v36, 0x400, v47
	v_cndmask_b32_e64 v32, v195, v2, s[12:13]
	v_add_u32_e32 v40, 0x800, v47
	ds_write2_b32 v36, v35, v34 offset1:136
	ds_write2_b32 v40, v33, v32 offset0:16 offset1:152
	v_mov_b32_e32 v4, v148
	v_mov_b32_e32 v5, v149
	v_mov_b32_e32 v6, v150
	v_mov_b32_e32 v7, v151
	v_mul_f32_e32 v39, 0x3e000000, v4
	v_mul_f32_e32 v38, 0x3e000000, v5
	ds_write2_b32 v36, v39, v38 offset0:64 offset1:200
	v_mul_f32_e32 v37, 0x3e000000, v6
	v_mul_f32_e32 v36, 0x3e000000, v7
	ds_write2_b32 v40, v37, v36 offset0:80 offset1:216
	v_mov_b32_e32 v6, v152
	v_mov_b32_e32 v7, v153
	v_mov_b32_e32 v4, v154
	v_mov_b32_e32 v5, v155
	s_mov_b64 s[2:3], exec
